# k18 + Hyena items: the 14 per-channel constant loads (conv + two gating stages) issued once after the tap loads instead of three load-then-wait sites
# baseline (speedup 1.0000x reference)
.LBB0_1227:
	s_or_b64 exec, exec, s[76:77]
	s_lshl_b64 s[80:81], s[74:75], 2
	s_add_u32 s76, s95, s80
	v_lshl_add_u32 v27, v145, 4, 0
	s_addc_u32 s77, s94, s81
	v_add_u32_e32 v27, 0x11400, v27
	s_add_u32 s78, s97, s80
	s_addc_u32 s79, s96, s81
	s_add_u32 s98, s31, s80
	s_addc_u32 s99, s30, s81
	global_load_dword v174, v35, s[76:77]
	global_load_dword v175, v1, s[76:77]
	global_load_dword v176, v35, s[78:79]
	global_load_dword v177, v124, s[76:77]
	global_load_dword v178, v126, s[76:77]
	global_load_dword v179, v126, s[78:79]
	global_load_dword v180, v127, s[76:77]
	global_load_dword v181, v128, s[76:77]
	global_load_dword v182, v35, s[98:99]
	global_load_dword v183, v126, s[98:99]
	global_load_dword v184, v129, s[78:79]
	global_load_dword v185, v129, s[76:77]
	global_load_dword v186, v130, s[76:77]
	global_load_dword v187, v131, s[76:77]
	s_waitcnt vmcnt(19)
	ds_write_b128 v27, v[2:5]
	s_waitcnt vmcnt(18)
	ds_write_b128 v27, v[6:9] offset:8192
	s_waitcnt vmcnt(17)
	ds_write_b128 v27, v[10:13] offset:16384
	s_waitcnt vmcnt(16)
	ds_write_b128 v27, v[14:17] offset:24576
	s_waitcnt vmcnt(15)
	ds_write_b128 v27, v[18:21] offset:32768
	s_waitcnt vmcnt(14)
	ds_write_b128 v27, v[22:25] offset:40960
	s_waitcnt lgkmcnt(0)
	s_barrier
	v_ashrrev_i32_e32 v142, 8, v145
	v_lshlrev_b32_e32 v150, 3, v138
	v_lshlrev_b32_e32 v27, 1, v138
	v_lshl_or_b32 v29, v142, 14, v150
	v_lshl_or_b32 v139, v142, 12, v27
	v_add_u32_e32 v141, 0x1d440, v29
	s_mov_b32 s28, 0
	v_lshl_or_b32 v140, v142, 11, v138
	v_mov_b32_e32 v27, v139
	v_mov_b32_e32 v29, v141
	s_waitcnt vmcnt(13)
	v_mov_b32_e32 v58, v174
	v_mov_b32_e32 v59, v174
	s_waitcnt vmcnt(12)
	v_mov_b32_e32 v60, v175
	v_mov_b32_e32 v61, v175
	s_waitcnt vmcnt(11)
	v_mov_b32_e32 v62, v176
	v_mov_b32_e32 v63, v176
	s_waitcnt vmcnt(10)
	v_mov_b32_e32 v64, v177
	v_mov_b32_e32 v65, v177

.LBB0_1339:
	s_or_b64 exec, exec, s[0:1]
	s_add_u32 s6, s31, s80
	s_addc_u32 s7, s30, s81
	ds_write_b64 v144, v[26:27] offset:26112
	ds_write_b64 v144, v[28:29] offset:28288
	ds_write_b64 v144, v[30:31] offset:30464
	ds_write_b64 v144, v[32:33] offset:32640
	s_waitcnt lgkmcnt(0)
	s_barrier
	v_mul_i32_i24_e32 v27, 0x4400, v142
	s_movk_i32 s0, 0x4400
	v_sub_u32_e32 v27, v152, v27
	v_mad_i32_i24 v29, v142, s0, v148
	v_lshlrev_b32_e32 v31, 3, v143
	v_add_u32_e32 v94, 0x8800, v27
	s_mov_b32 s80, 0
	v_mov_b32_e32 v43, v141
	v_add3_u32 v45, v29, v31, v150
	v_mov_b32_e32 v47, v94
	v_mov_b32_e32 v49, v139
	s_waitcnt vmcnt(4)
	v_mov_b32_e32 v26, v178
	v_mov_b32_e32 v27, v178
	s_waitcnt vmcnt(3)
	v_mov_b32_e32 v28, v179
	v_mov_b32_e32 v29, v179
	s_waitcnt vmcnt(2)
	v_mov_b32_e32 v30, v180
	v_mov_b32_e32 v31, v180
	s_waitcnt vmcnt(1)
	v_mov_b32_e32 v32, v181
	v_mov_b32_e32 v33, v181
	s_waitcnt vmcnt(0)
	v_mov_b32_e32 v72, v182
	v_mov_b32_e32 v73, v182

.LBB0_1421:
	s_or_b64 exec, exec, s[0:1]
	ds_write_b64 v144, v[26:27] offset:26112
	ds_write_b64 v144, v[28:29] offset:28288
	ds_write_b64 v144, v[30:31] offset:30464
	ds_write_b64 v144, v[32:33] offset:32640
	s_waitcnt lgkmcnt(0)
	s_barrier
	v_mul_i32_i24_e32 v27, 0x880, v142
	s_lshl_b64 s[0:1], s[74:75], 15
	v_or_b32_e32 v27, v143, v27
	s_add_u32 s4, s27, s0
	v_add_u32_e32 v27, v27, v138
	s_addc_u32 s5, s26, s1
	v_lshl_add_u32 v34, v27, 3, v148
	s_mov_b32 s6, 0
	s_waitcnt vmcnt(4)
	v_mov_b32_e32 v26, v183
	v_mov_b32_e32 v27, v183
	s_waitcnt vmcnt(3)
	v_mov_b32_e32 v28, v184
	v_mov_b32_e32 v29, v184
	s_waitcnt vmcnt(2)
	v_mov_b32_e32 v30, v185
	v_mov_b32_e32 v31, v185
	s_waitcnt vmcnt(1)
	v_mov_b32_e32 v32, v186
	v_mov_b32_e32 v33, v186
	s_waitcnt vmcnt(0)
	v_mov_b32_e32 v36, v187
	v_mov_b32_e32 v37, v187

.LBB0_3292:
	s_lshl_b64 s[80:81], s[70:71], 2
	s_add_u32 s72, s88, s80
	v_lshl_add_u32 v27, v133, 4, 0
	s_addc_u32 s73, s89, s81
	v_add_u32_e32 v27, 0x11400, v27
	s_add_u32 s74, s26, s80
	s_addc_u32 s75, s27, s81
	s_add_u32 s98, s33, s80
	s_addc_u32 s99, s3, s81
	global_load_dword v174, v35, s[72:73]
	global_load_dword v175, v1, s[72:73]
	global_load_dword v176, v35, s[74:75]
	global_load_dword v177, v118, s[72:73]
	global_load_dword v178, v119, s[72:73]
	global_load_dword v179, v119, s[74:75]
	global_load_dword v180, v120, s[72:73]
	global_load_dword v181, v121, s[72:73]
	global_load_dword v182, v35, s[98:99]
	global_load_dword v183, v119, s[98:99]
	global_load_dword v184, v122, s[74:75]
	global_load_dword v185, v122, s[72:73]
	global_load_dword v186, v123, s[72:73]
	global_load_dword v187, v124, s[72:73]
	s_waitcnt vmcnt(19)
	ds_write_b128 v27, v[2:5]
	s_waitcnt vmcnt(18)
	ds_write_b128 v27, v[6:9] offset:8192
	s_waitcnt vmcnt(17)
	ds_write_b128 v27, v[10:13] offset:16384
	s_waitcnt vmcnt(16)
	ds_write_b128 v27, v[14:17] offset:24576
	s_waitcnt vmcnt(15)
	ds_write_b128 v27, v[18:21] offset:32768
	s_waitcnt vmcnt(14)
	ds_write_b128 v27, v[22:25] offset:40960
	s_waitcnt lgkmcnt(0)
	s_barrier
	v_ashrrev_i32_e32 v130, 8, v133
	v_lshlrev_b32_e32 v137, 3, v126
	v_lshlrev_b32_e32 v27, 1, v126
	v_lshl_or_b32 v29, v130, 14, v137
	v_lshl_or_b32 v127, v130, 12, v27
	v_add_u32_e32 v129, 0x1d440, v29
	s_mov_b32 s4, 0
	v_lshl_or_b32 v128, v130, 11, v126
	v_mov_b32_e32 v27, v127
	v_mov_b32_e32 v38, v129
	s_waitcnt vmcnt(13)
	v_mov_b32_e32 v28, v174
	v_mov_b32_e32 v29, v174
	s_waitcnt vmcnt(12)
	v_mov_b32_e32 v30, v175
	v_mov_b32_e32 v31, v175
	s_waitcnt vmcnt(11)
	v_mov_b32_e32 v32, v176
	v_mov_b32_e32 v33, v176
	s_waitcnt vmcnt(10)
	v_mov_b32_e32 v36, v177
	v_mov_b32_e32 v37, v177

.LBB0_3408:
	s_or_b64 exec, exec, s[0:1]
	s_add_u32 s6, s33, s80
	s_addc_u32 s7, s3, s81
	ds_write_b64 v132, v[28:29] offset:26112
	ds_write_b64 v132, v[30:31] offset:28288
	ds_write_b64 v132, v[32:33] offset:30464
	ds_write_b64 v132, v[70:71] offset:32640
	s_waitcnt lgkmcnt(0)
	s_barrier
	v_mul_i32_i24_e32 v29, 0x4400, v130
	s_movk_i32 s0, 0x4400
	v_sub_u32_e32 v29, v138, v29
	v_mad_i32_i24 v31, v130, s0, v108
	v_lshlrev_b32_e32 v33, 3, v131
	v_add_u32_e32 v96, 0x8800, v29
	s_mov_b32 s15, 0
	v_mov_b32_e32 v27, v129
	v_add3_u32 v43, v31, v33, v137
	v_mov_b32_e32 v45, v96
	v_mov_b32_e32 v47, v127
	s_waitcnt vmcnt(4)
	v_mov_b32_e32 v28, v178
	v_mov_b32_e32 v29, v178
	s_waitcnt vmcnt(3)
	v_mov_b32_e32 v30, v179
	v_mov_b32_e32 v31, v179
	s_waitcnt vmcnt(2)
	v_mov_b32_e32 v32, v180
	v_mov_b32_e32 v33, v180
	s_waitcnt vmcnt(1)
	v_mov_b32_e32 v70, v181
	v_mov_b32_e32 v71, v181
	s_waitcnt vmcnt(0)
	v_mov_b32_e32 v72, v182
	v_mov_b32_e32 v73, v182

.LBB0_3494:
	s_or_b64 exec, exec, s[0:1]
	ds_write_b64 v132, v[26:27] offset:26112
	ds_write_b64 v132, v[28:29] offset:28288
	ds_write_b64 v132, v[30:31] offset:30464
	ds_write_b64 v132, v[32:33] offset:32640
	s_waitcnt lgkmcnt(0)
	s_barrier
	v_mul_i32_i24_e32 v27, 0x880, v130
	s_lshl_b64 s[0:1], s[70:71], 15
	v_or_b32_e32 v27, v131, v27
	s_add_u32 s4, s31, s0
	v_add_u32_e32 v27, v27, v126
	s_addc_u32 s5, s30, s1
	v_lshl_add_u32 v34, v27, 3, v108
	s_mov_b32 s6, 0
	s_waitcnt vmcnt(4)
	v_mov_b32_e32 v26, v183
	v_mov_b32_e32 v27, v183
	s_waitcnt vmcnt(3)
	v_mov_b32_e32 v28, v184
	v_mov_b32_e32 v29, v184
	s_waitcnt vmcnt(2)
	v_mov_b32_e32 v30, v185
	v_mov_b32_e32 v31, v185
	s_waitcnt vmcnt(1)
	v_mov_b32_e32 v32, v186
	v_mov_b32_e32 v33, v186
	s_waitcnt vmcnt(0)
	v_mov_b32_e32 v36, v187
	v_mov_b32_e32 v37, v187
